# v_m9 + prep: mla_up tiles remapped so the 7 column tiles of a row-block run on blocks of the same XCD
# speedup vs baseline: 1.0101x; 1.0053x over previous
; DI int otid() { int t; asm volatile("v_mov_b32 %0, %1" : "=v"(t) : "v"((int)threadIdx.x)); return t; }
; DI void mla_up_tile(const Params& p, int l, int tm, int tn, char* smem) {
;   u16* sA = (u16*)smem; u16* sW = sA + 128 * 72; float* sC = (float*)smem;
;   float* sRs = (float*)(smem + 73728);
;   const int tid = otid();
;   const bool isq = tn < 3;
;   const u16* Pt = p.P + (long)tm * 128 * NP1;
;   {
;     int row = tid >> 1, part = tid & 1;
;     int n = isq ? 128 : 64;
;     const u16* s = Pt + (long)row * NP1 + (isq ? C_QLAT : C_KVLAT) + part * n;
;     float ss = 0.f;
;     for (int q = 0; q < n / 8; q++) {
;       u32x4 w = *(const u32x4*)(s + q * 8);
;       float v[8]; unpack8(w, v);
; #pragma unroll
;       for (int e = 0; e < 8; e++) ss += v[e] * v[e];
;     }
;     ss += __int_as_float(__builtin_amdgcn_mov_dpp(__float_as_int(ss), 0xB1, 0xf, 0xf, true));
;     if (part == 0) sRs[row] = rsqrtf(ss * (isq ? 1.f / 256.f : 1.f / 128.f) + 1e-6f);
; DI void phase_prep(const Params& p, int l, int half, char* smem) {
;     ...
;   for (int it = blockIdx.x; it < total; it += gridDim.x) {
;     if (it < n_rw) rwkv_prep_group(p, l, it, smem);
;     else if (it < n_rw + n_mla) { int q = it - n_rw; mla_up_tile(p, l, q / 7, q % 7, smem); }
.LBB0_447:
	s_andn2_b64 vcc, exec, s[0:1]
	s_cbranch_vccnz .LBB0_878
	s_add_i32 s0, s68, 0xf780
	s_and_b32 s0, s0, 0xffff
	s_and_b32 s1, s0, 7
	s_mulk_i32 s1, 0x77
	s_lshr_b32 s0, s0, 3
	s_add_i32 s0, s0, s1
	s_and_b32 s1, s0, 0xffff
	s_mulk_i32 s1, 0x2493
	s_lshr_b32 s1, s1, 16
	s_sub_i32 s12, s0, s1
	s_bfe_u32 s12, s12, 0xf0001
	s_add_i32 s12, s12, s1
	s_lshr_b32 s1, s12, 2
	s_and_b32 s50, s1, 0x3fff
	s_mul_i32 s1, s50, 7
	s_sub_i32 s0, s0, s1
	s_and_b32 s12, s0, 0xffff
	s_cmp_gt_u32 s12, 2
	s_mul_i32 s26, s50, 0x78000
	v_readlane_b32 s52, v255, 1
	s_cselect_b64 s[38:39], -1, 0
	s_lshl_b64 s[0:1], s[26:27], 1
	v_readlane_b32 s62, v255, 11
	v_readlane_b32 s63, v255, 12
	s_add_u32 s0, s62, s0
	s_addc_u32 s1, s63, s1
	s_cmp_lt_u32 s12, 3
	s_cselect_b64 s[36:37], -1, 0
	s_and_b64 s[48:49], s[36:37], exec
	v_mov_b32 v72, v198
	s_waitcnt vmcnt(3)
	v_mov_b64_e32 v[0:1], s[0:1]
	v_ashrrev_i32_e32 v2, 1, v72
	v_and_b32_e32 v3, 1, v72
	s_cselect_b32 s13, 7, 6
	v_mad_i64_i32 v[0:1], s[48:49], v2, s25, v[0:1]
	s_cselect_b32 s26, 0, 0x200
	s_waitcnt vmcnt(2)
	v_lshlrev_b32_e32 v4, s13, v3
	v_lshl_add_u64 v[0:1], v[0:1], 0, s[26:27]
	v_lshlrev_b32_e32 v176, 1, v4
	v_lshl_add_u64 v[0:1], v[0:1], 0, v[176:177]
	s_cselect_b32 s13, 16, 8
	v_mov_b32_e32 v4, 0
	v_readlane_b32 s53, v255, 2
	v_readlane_b32 s54, v255, 3
	v_readlane_b32 s55, v255, 4
	v_readlane_b32 s56, v255, 5
	v_readlane_b32 s57, v255, 6
	v_readlane_b32 s58, v255, 7
	v_readlane_b32 s59, v255, 8
	v_readlane_b32 s60, v255, 9
	v_readlane_b32 s61, v255, 10
	v_readlane_b32 s64, v255, 13
	v_readlane_b32 s65, v255, 14
	v_readlane_b32 s66, v255, 15
	v_readlane_b32 s67, v255, 16
